# prep: hb rows stored write-through (sc1) so the first grid barrier's release fence has less dirty L2 to write back
# speedup vs baseline: 1.0025x; 1.0025x over previous
.LBB0_41:
	v_lshl_add_u32 v44, s30, 4, v43
	v_ashrrev_i32_e32 v45, 31, v44
	v_lshlrev_b64 v[2:3], 12, v[44:45]
	v_lshl_add_u64 v[2:3], v[36:37], 0, v[2:3]
	global_load_dwordx4 v[30:33], v[2:3], off nt
	global_load_dwordx4 v[26:29], v[2:3], off offset:1024 nt
	global_load_dwordx4 v[22:25], v[2:3], off offset:2048 nt
	global_load_dwordx4 v[18:21], v[2:3], off offset:3072 nt
	v_add_co_u32_e32 v2, vcc, 0x1000, v2
	v_lshlrev_b64 v[44:45], 11, v[44:45]
	s_nop 0
	v_addc_co_u32_e32 v3, vcc, 0, v3, vcc
	global_load_dwordx4 v[14:17], v[2:3], off nt
	global_load_dwordx4 v[10:13], v[2:3], off offset:1024 nt
	global_load_dwordx4 v[6:9], v[2:3], off offset:2048 nt
	s_nop 0
	global_load_dwordx4 v[2:5], v[2:3], off offset:3072 nt
	s_nop 0
	v_lshl_add_u64 v[44:45], v[40:41], 0, v[44:45]
	s_waitcnt vmcnt(7)
	v_mov_b32_e32 v56, v31
	s_waitcnt vmcnt(6)
	v_mov_b32_e32 v57, v27
	s_waitcnt vmcnt(5)
	v_mov_b32_e32 v64, v23
	s_waitcnt vmcnt(4)
	v_mov_b32_e32 v65, v19
	v_mov_b32_e32 v54, v30
	v_mov_b32_e32 v55, v26
	v_mov_b32_e32 v62, v22
	v_mov_b32_e32 v63, v18
	v_pk_mul_f32 v[56:57], v[56:57], v[56:57]
	v_pk_mul_f32 v[64:65], v[64:65], v[64:65]
	v_mov_b32_e32 v58, v32
	v_mov_b32_e32 v59, v28
	v_pk_fma_f32 v[54:55], v[54:55], v[54:55], v[56:57]
	v_pk_fma_f32 v[56:57], v[62:63], v[62:63], v[64:65]
	s_waitcnt vmcnt(3)
	v_mov_b32_e32 v64, v15
	s_waitcnt vmcnt(2)
	v_mov_b32_e32 v65, v11
	v_mov_b32_e32 v60, v33
	v_mov_b32_e32 v61, v29
	v_mov_b32_e32 v66, v24
	v_mov_b32_e32 v67, v20
	v_mov_b32_e32 v62, v14
	v_mov_b32_e32 v63, v10
	s_waitcnt vmcnt(1)
	v_mov_b32_e32 v74, v7
	s_waitcnt vmcnt(0)
	v_mov_b32_e32 v75, v3
	v_pk_fma_f32 v[54:55], v[58:59], v[58:59], v[54:55]
	v_pk_mul_f32 v[58:59], v[64:65], v[64:65]
	v_mov_b32_e32 v68, v25
	v_mov_b32_e32 v69, v21
	v_mov_b32_e32 v70, v16
	v_mov_b32_e32 v71, v12
	v_mov_b32_e32 v72, v6
	v_mov_b32_e32 v73, v2
	v_pk_fma_f32 v[56:57], v[66:67], v[66:67], v[56:57]
	v_pk_mul_f32 v[64:65], v[74:75], v[74:75]
	v_pk_fma_f32 v[54:55], v[60:61], v[60:61], v[54:55]
	v_pk_fma_f32 v[58:59], v[62:63], v[62:63], v[58:59]
	v_mov_b32_e32 v76, v17
	v_mov_b32_e32 v77, v13
	v_mov_b32_e32 v78, v8
	v_mov_b32_e32 v79, v4
	v_pk_fma_f32 v[56:57], v[68:69], v[68:69], v[56:57]
	v_pk_fma_f32 v[60:61], v[72:73], v[72:73], v[64:65]
	v_pk_fma_f32 v[58:59], v[70:71], v[70:71], v[58:59]
	v_add_f32_e32 v34, v54, v55
	v_mov_b32_e32 v80, v9
	v_mov_b32_e32 v81, v5
	v_pk_fma_f32 v[54:55], v[78:79], v[78:79], v[60:61]
	v_pk_fma_f32 v[58:59], v[76:77], v[76:77], v[58:59]
	v_add_f32_e32 v34, v34, v56
	v_pk_fma_f32 v[54:55], v[80:81], v[80:81], v[54:55]
	v_add_f32_e32 v34, v34, v57
	v_add_f32_e32 v49, v58, v59
	v_add_f32_e32 v49, v49, v54
	v_mov_b32_e32 v54, v34
	v_add_f32_e32 v49, v49, v55
	s_nop 0
	v_mov_b32_dpp v54, v54 quad_perm:[1,0,3,2] row_mask:0xf bank_mask:0xf
	v_add_f32_e32 v34, v34, v54
	v_mov_b32_e32 v54, v49
	v_mov_b32_e32 v55, v34
	s_nop 0
	v_mov_b32_dpp v54, v54 quad_perm:[1,0,3,2] row_mask:0xf bank_mask:0xf
	v_add_f32_e32 v49, v49, v54
	v_mov_b32_dpp v55, v55 quad_perm:[2,3,0,1] row_mask:0xf bank_mask:0xf
	v_mov_b32_e32 v54, v49
	v_add_f32_e32 v34, v34, v55
	v_mov_b32_e32 v55, v34
	v_mov_b32_dpp v54, v54 quad_perm:[2,3,0,1] row_mask:0xf bank_mask:0xf
	v_add_f32_e32 v49, v49, v54
	v_mov_b32_dpp v55, v55 row_half_mirror row_mask:0xf bank_mask:0xf
	v_mov_b32_e32 v54, v49
	v_add_f32_e32 v34, v34, v55
	v_mov_b32_e32 v55, v34
	v_mov_b32_dpp v54, v54 row_half_mirror row_mask:0xf bank_mask:0xf
	v_add_f32_e32 v49, v49, v54
	v_mov_b32_dpp v55, v55 row_mirror row_mask:0xf bank_mask:0xf
	v_mov_b32_e32 v56, v49
	v_add_f32_e32 v34, v34, v55
	s_nop 0
	v_mov_b32_dpp v56, v56 row_mirror row_mask:0xf bank_mask:0xf
	v_readlane_b32 s0, v34, 0
	v_readlane_b32 s6, v34, 16
	v_readlane_b32 s1, v34, 32
	v_readlane_b32 s24, v34, 48
	v_add_f32_e32 v34, v49, v56
	v_mov_b32_e32 v54, s6
	v_mov_b32_e32 v55, s24
	v_readlane_b32 s6, v34, 16
	v_readlane_b32 s24, v34, 48
	v_pk_add_f32 v[54:55], s[0:1], v[54:55]
	v_readlane_b32 s0, v34, 0
	v_readlane_b32 s1, v34, 32
	v_mov_b32_e32 v56, s6
	v_mov_b32_e32 v57, s24
	v_pk_add_f32 v[56:57], s[0:1], v[56:57]
	v_mov_b32_e32 v59, v54
	v_mov_b32_e32 v58, v56
	v_mov_b32_e32 v54, v57
	v_pk_add_f32 v[54:55], v[58:59], v[54:55]
	s_nop 0
	v_pk_fma_f32 v[54:55], v[54:55], s[22:23], v[42:43] op_sel_hi:[1,0,0]
	s_nop 0
	v_mul_f32_e32 v34, 0x4b800000, v55
	v_cmp_gt_f32_e32 vcc, s23, v55
	s_nop 1
	v_cndmask_b32_e32 v34, v55, v34, vcc
	v_rsq_f32_e32 v34, v34
	s_nop 0
	v_mul_f32_e32 v49, 0x45800000, v34
	v_cndmask_b32_e32 v34, v34, v49, vcc
	v_cmp_gt_f32_e32 vcc, s23, v54
	v_mul_f32_e32 v49, 0x4b800000, v54
	v_pk_mul_f32 v[32:33], v[32:33], v[34:35] op_sel_hi:[1,0]
	v_cndmask_b32_e32 v49, v54, v49, vcc
	v_rsq_f32_e32 v49, v49
	v_pk_mul_f32 v[30:31], v[30:31], v[34:35] op_sel_hi:[1,0]
	v_mul_f32_e32 v56, 0x45800000, v49
	v_cndmask_b32_e32 v56, v49, v56, vcc
	v_pk_mul_f32 v[32:33], v[32:33], v[86:87]
	v_pk_mul_f32 v[30:31], v[30:31], v[84:85]
	v_cvt_pk_bf16_f32 v33, v32, v33
	v_cvt_pk_bf16_f32 v32, v30, v31
	global_store_dwordx2 v[44:45], v[32:33], off sc1
	v_pk_mul_f32 v[28:29], v[28:29], v[34:35] op_sel_hi:[1,0]
	v_pk_mul_f32 v[26:27], v[26:27], v[34:35] op_sel_hi:[1,0]
	v_pk_mul_f32 v[28:29], v[28:29], v[90:91]
	v_pk_mul_f32 v[26:27], v[26:27], v[88:89]
	v_cvt_pk_bf16_f32 v29, v28, v29
	v_cvt_pk_bf16_f32 v28, v26, v27
	global_store_dwordx2 v[44:45], v[28:29], off offset:512 sc1
	v_pk_mul_f32 v[24:25], v[24:25], v[34:35] op_sel_hi:[1,0]
	v_pk_mul_f32 v[22:23], v[22:23], v[34:35] op_sel_hi:[1,0]
	v_pk_mul_f32 v[24:25], v[24:25], v[94:95]
	v_pk_mul_f32 v[22:23], v[22:23], v[92:93]
	v_cvt_pk_bf16_f32 v25, v24, v25
	v_cvt_pk_bf16_f32 v24, v22, v23
	global_store_dwordx2 v[44:45], v[24:25], off offset:1024 sc1
	v_pk_mul_f32 v[20:21], v[20:21], v[34:35] op_sel_hi:[1,0]
	v_pk_mul_f32 v[18:19], v[18:19], v[34:35] op_sel_hi:[1,0]
	v_pk_mul_f32 v[20:21], v[20:21], v[98:99]
	v_pk_mul_f32 v[18:19], v[18:19], v[96:97]
	v_cvt_pk_bf16_f32 v21, v20, v21
	v_cvt_pk_bf16_f32 v20, v18, v19
	global_store_dwordx2 v[44:45], v[20:21], off offset:1536 sc1
	v_pk_mul_f32 v[16:17], v[16:17], v[56:57] op_sel_hi:[1,0]
	v_pk_mul_f32 v[14:15], v[14:15], v[56:57] op_sel_hi:[1,0]
	v_pk_mul_f32 v[16:17], v[16:17], v[86:87]
	v_pk_mul_f32 v[14:15], v[14:15], v[84:85]
	v_cvt_pk_bf16_f32 v17, v16, v17
	v_cvt_pk_bf16_f32 v16, v14, v15
	global_store_dwordx2 v[44:45], v[16:17], off offset:2048 sc1
	v_pk_mul_f32 v[12:13], v[12:13], v[56:57] op_sel_hi:[1,0]
	v_pk_mul_f32 v[10:11], v[10:11], v[56:57] op_sel_hi:[1,0]
	v_pk_mul_f32 v[12:13], v[12:13], v[90:91]
	v_pk_mul_f32 v[10:11], v[10:11], v[88:89]
	v_cvt_pk_bf16_f32 v13, v12, v13
	v_cvt_pk_bf16_f32 v12, v10, v11
	global_store_dwordx2 v[44:45], v[12:13], off offset:2560 sc1
	v_pk_mul_f32 v[8:9], v[8:9], v[56:57] op_sel_hi:[1,0]
	v_pk_mul_f32 v[6:7], v[6:7], v[56:57] op_sel_hi:[1,0]
	v_pk_mul_f32 v[8:9], v[8:9], v[94:95]
	v_pk_mul_f32 v[6:7], v[6:7], v[92:93]
	v_cvt_pk_bf16_f32 v9, v8, v9
	v_cvt_pk_bf16_f32 v8, v6, v7
	global_store_dwordx2 v[44:45], v[8:9], off offset:3072 sc1
	v_pk_mul_f32 v[4:5], v[4:5], v[56:57] op_sel_hi:[1,0]
	v_pk_mul_f32 v[2:3], v[2:3], v[56:57] op_sel_hi:[1,0]
	v_pk_mul_f32 v[4:5], v[4:5], v[98:99]
	v_pk_mul_f32 v[2:3], v[2:3], v[96:97]
	v_cvt_pk_bf16_f32 v5, v4, v5
	v_cvt_pk_bf16_f32 v4, v2, v3
	global_store_dwordx2 v[44:45], v[4:5], off offset:3584 sc1
	s_branch .LBB0_7
